# mixer_out: next unit's gate/Qeff/state/O_local lines prefetched into L2 during the current unit (dead-register destination)
# speedup vs baseline: 1.0062x; 1.0062x over previous
; #define LAS __attribute__((address_space(3)))
; __device__ __forceinline__ void mixer_out_phase(const Ctx& X, LAS unsigned char* lds, int layer, int tid, int wave, int lane) {
;     ...
;     for (int u = blockIdx.x; u < 1536; u += gridDim.x) {
;         asm volatile("" : "+v"(lane), "+v"(tid));
;         LAS bf16_t* GT = opq((LAS bf16_t*)lds);
;         const int r = lane & 15, q = lane >> 4, h = wave >> 1, half = wave & 1;
;         const int mixer = u >> 9, rem = u & 511, b = rem >> 7, c = rem & 127;
;         const int uid = unit_id(mixer, b, h, c);
;         const int goff = mixer == 0 ? C_RG : (mixer == 1 ? C_GG : C_HG), moff = mixer == 0 ? 0 : (mixer == 1 ? 512 : 768);
;         const size_t row0 = (size_t)b * T + c * 64;
;         u32x4 gv[4];
; #pragma unroll
;         for (int n = 0; n < 4; ++n) { const int idx = tid + 512 * n; gv[n] = *(const u32x4*)(proj + (row0 + (idx >> 5)) * LDP + goff + (idx & 31) * 8); }
;         const bf16_t* qe = WSP(const bf16_t, WS_QEFF) + (size_t)uid * 4096;
;         const bf16_t* st = WSP(const bf16_t, WS_BCS) + (size_t)uid * 4096;
;         bf16x8 a[2][2], bb[4][2]; u32x4 ov[2][2];
; #pragma unroll
;         for (int rt = 0; rt < 2; ++rt) { const int rt4 = 2 * half + rt;
; #pragma unroll
;             for (int ks = 0; ks < 2; ++ks) a[rt][ks] = *(const bf16x8*)(qe + (16 * rt4 + r) * 64 + ks * 32 + q * 8);
;             const u32x4* ol = (const u32x4*)(WSP(const bf16_t, WS_OLOC) + ((size_t)uid * 4 + rt4) * 1024 + lane * 16); ov[rt][0] = ol[0]; ov[rt][1] = ol[1]; }
; #pragma unroll
;         for (int ct = 0; ct < 4; ++ct)
; #pragma unroll
;             for (int ks = 0; ks < 2; ++ks) { const bf16_t* tb = st + (size_t)((ct * 4 + 2 * ks + (q >> 1)) * 64) * 4;
;                 const u32x2 lo = *(const u32x2*)(tb + ((2 * (q & 1)) * 16 + r) * 4), hi = *(const u32x2*)(tb + ((2 * (q & 1) + 1) * 16 + r) * 4);
;                 bb[ct][ks] = __builtin_bit_cast(bf16x8, (u32x4){lo.x, lo.y, hi.x, hi.y}); }
;         const float* nw = mixer == 0 ? X.in[3] + layer * 256 + h * 64 : (mixer == 1 ? X.in[11] + layer * 64 : X.in[13] + layer * 64);
;         float wv[4];
; #pragma unroll
;         for (int ct = 0; ct < 4; ++ct) wv[ct] = nw[16 * ct + r];
; #pragma unroll
;         for (int n = 0; n < 4; ++n) { const int idx = tid + 512 * n; *(LAS u32x4*)(GT + (idx >> 5) * GP + (idx & 31) * 8) = gv[n]; }
;         LBAR();
.LBB0_888:
	s_ashr_i32 s6, s10, 9
	s_cmp_eq_u32 s6, 1
	s_movk_i32 s0, 0xd00
	s_cselect_b32 s7, 0x900, s0
	s_movk_i32 s0, 0x200
	s_cselect_b32 s11, s0, 0x300
	s_cselect_b32 s12, s50, s54
	s_cselect_b32 s13, s51, s55
	s_cmpk_lt_u32 s10, 0x200
	s_cselect_b64 s[0:1], -1, 0
	s_and_b64 s[0:1], s[0:1], exec
	s_cselect_b32 s11, 0, s11
	s_add_u32 s12, s12, s4
	s_addc_u32 s13, s13, s5
	s_cmpk_lt_u32 s10, 0x200
	s_cselect_b64 vcc, -1, 0
	s_and_b64 s[0:1], vcc, exec
	s_cselect_b32 s7, 0x300, s7
	s_cselect_b32 s1, s9, s13
	s_cselect_b32 s0, s8, s12
	s_bfe_u32 s12, s10, 0x20007
	s_and_b32 s13, s10, 0x7f
	s_lshl_b32 s14, s12, 9
	s_lshl_b32 s15, s6, 11
	s_lshl_b32 s6, s12, 13
	s_lshl_b32 s12, s13, 6
	s_or_b32 s16, s6, s12
	s_lshl_b32 s6, s7, 1
	s_add_u32 s6, s76, s6
	s_waitcnt vmcnt(0)
	v_lshlrev_b32_e32 v6, 4, v104
	v_ashrrev_i32_e32 v94, 5, v104
	s_addc_u32 s7, s77, 0
	v_and_b32_e32 v156, 0x1f0, v6
	v_ashrrev_i32_e32 v95, 31, v94
	v_lshl_add_u64 v[6:7], s[6:7], 0, v[156:157]
	v_lshl_add_u64 v[92:93], s[16:17], 0, v[94:95]
	v_mov_b32_e32 v108, v157
	v_mad_i64_i32 v[8:9], s[6:7], v92, s71, v[6:7]
	global_load_dwordx4 v[62:65], v[8:9], off
	v_add_u32_e32 v8, 0x200, v104
	v_ashrrev_i32_e32 v98, 5, v8
	v_ashrrev_i32_e32 v99, 31, v98
	v_lshl_add_u64 v[90:91], s[16:17], 0, v[98:99]
	v_mad_i64_i32 v[8:9], s[6:7], v90, s71, v[6:7]
	global_load_dwordx4 v[74:77], v[8:9], off
	v_add_u32_e32 v8, 0x400, v104
	v_ashrrev_i32_e32 v100, 5, v8
	v_ashrrev_i32_e32 v101, 31, v100
	v_lshl_add_u64 v[88:89], s[16:17], 0, v[100:101]
	v_mad_i64_i32 v[8:9], s[6:7], v88, s71, v[6:7]
	global_load_dwordx4 v[78:81], v[8:9], off
	v_add_u32_e32 v8, 0x600, v104
	v_ashrrev_i32_e32 v102, 5, v8
	v_ashrrev_i32_e32 v103, 31, v102
	v_lshl_add_u64 v[86:87], s[16:17], 0, v[102:103]
	v_mad_i64_i32 v[6:7], s[6:7], v86, s71, v[6:7]
	s_or_b32 s6, s13, s23
	s_add_i32 s6, s6, s15
	s_add_i32 s6, s6, s14
	s_ashr_i32 s7, s6, 31
	s_waitcnt vmcnt(14)
	v_ashrrev_i32_e32 v110, 4, v105
	s_lshl_b64 s[6:7], s[6:7], 13
	global_load_dwordx4 v[82:85], v[6:7], off
	s_add_u32 s12, s89, s6
	v_lshlrev_b32_e32 v6, 3, v110
	s_addc_u32 s13, s78, s7
	v_ashrrev_i32_e32 v7, 31, v6
	v_and_b32_e32 v109, 15, v105
	v_lshl_add_u64 v[6:7], v[6:7], 1, s[12:13]
	s_add_u32 s12, s19, s6
	s_addc_u32 s13, s20, s7
	s_lshl_b32 s16, s21, 1
	v_lshlrev_b32_e32 v22, 7, v110
	v_lshlrev_b32_e32 v95, 2, v109
	s_add_u32 s6, s74, s6
	v_and_or_b32 v22, v22, s33, v95
	s_addc_u32 s7, s75, s7
	v_lshlrev_b32_e32 v22, 1, v22
	v_mov_b32_e32 v23, v157
	v_lshlrev_b32_e32 v12, 6, v109
	v_lshlrev_b32_e32 v8, 4, v105
	v_lshl_add_u64 v[50:51], s[6:7], 0, v[22:23]
	v_lshlrev_b32_e32 v22, 1, v105
	v_ashrrev_i32_e32 v9, 31, v8
	v_or_b32_e32 v10, s21, v12
	v_and_b32_e32 v52, 0xffffffc0, v22
	v_lshl_add_u64 v[8:9], v[8:9], 1, s[12:13]
	v_lshlrev_b32_e32 v10, 1, v10
	v_mov_b32_e32 v11, v157
	v_add_u32_e32 v26, 0x80, v52
	v_add_u32_e32 v30, 0x100, v52
	v_lshl_add_u64 v[10:11], v[6:7], 0, v[10:11]
	v_lshl_add_u64 v[18:19], v[8:9], 0, s[16:17]
	v_add_lshl_u32 v8, v12, s21, 1
	v_mov_b32_e32 v9, v157
	v_ashrrev_i32_e32 v53, 31, v52
	v_ashrrev_i32_e32 v27, 31, v26
	v_ashrrev_i32_e32 v31, 31, v30
	global_load_dwordx4 v[66:69], v[10:11], off
	global_load_dwordx4 v[70:73], v[10:11], off offset:64
	global_load_dwordx4 v[54:57], v[18:19], off offset:16
	global_load_dwordx4 v[58:61], v[18:19], off
	v_lshl_add_u64 v[10:11], v[6:7], 0, v[8:9]
	s_waitcnt vmcnt(12)
	v_lshl_add_u64 v[24:25], v[52:53], 3, v[50:51]
	v_lshl_add_u64 v[28:29], v[26:27], 3, v[50:51]
	v_lshl_add_u64 v[32:33], v[30:31], 3, v[50:51]
	global_load_dwordx4 v[6:9], v[10:11], off offset:2048
	s_nop 0
	global_load_dwordx4 v[10:13], v[10:11], off offset:2112
	s_nop 0
	global_load_dwordx4 v[14:17], v[18:19], off offset:2064
	s_nop 0
	global_load_dwordx4 v[18:21], v[18:19], off offset:2048
	s_nop 0
	global_load_dwordx2 v[22:23], v[24:25], off
	s_nop 0
	global_load_dwordx2 v[24:25], v[24:25], off offset:128
	s_nop 0
	global_load_dwordx2 v[26:27], v[28:29], off
	s_nop 0
	global_load_dwordx2 v[28:29], v[28:29], off offset:128
	s_nop 0
	global_load_dwordx2 v[30:31], v[32:33], off
	s_nop 0
	global_load_dwordx2 v[32:33], v[32:33], off offset:128
	v_add_u32_e32 v34, 0x180, v52
	v_add_u32_e32 v38, 0x200, v52
	v_add_u32_e32 v42, 0x280, v52
	v_add_u32_e32 v46, 0x300, v52
	v_ashrrev_i32_e32 v35, 31, v34
	v_ashrrev_i32_e32 v39, 31, v38
	v_ashrrev_i32_e32 v43, 31, v42
	v_ashrrev_i32_e32 v47, 31, v46
	v_lshl_add_u64 v[36:37], v[34:35], 3, v[50:51]
	v_lshl_add_u64 v[40:41], v[38:39], 3, v[50:51]
	v_lshl_add_u64 v[44:45], v[42:43], 3, v[50:51]
	v_lshl_add_u64 v[48:49], v[46:47], 3, v[50:51]
	global_load_dwordx2 v[34:35], v[36:37], off
	s_nop 0
	global_load_dwordx2 v[36:37], v[36:37], off offset:128
	s_nop 0
	global_load_dwordx2 v[38:39], v[40:41], off
	s_nop 0
	global_load_dwordx2 v[40:41], v[40:41], off offset:128
	s_nop 0
	global_load_dwordx2 v[42:43], v[44:45], off
	s_nop 0
	global_load_dwordx2 v[44:45], v[44:45], off offset:128
	s_nop 0
	global_load_dwordx2 v[46:47], v[48:49], off
	s_nop 0
	global_load_dwordx2 v[48:49], v[48:49], off offset:128
	v_add_u32_e32 v52, 0x380, v52
	v_ashrrev_i32_e32 v53, 31, v52
	v_lshl_add_u64 v[52:53], v[52:53], 3, v[50:51]
	global_load_dwordx2 v[50:51], v[52:53], off
	s_nop 0
	global_load_dwordx2 v[52:53], v[52:53], off offset:128
	v_add_u32_e32 v112, v108, v156
	global_load_dword v106, v95, s[0:1]
	global_load_dword v103, v95, s[0:1] offset:64
	global_load_dword v101, v95, s[0:1] offset:128
	global_load_dword v99, v95, s[0:1] offset:192
	v_mad_u64_u32 v[96:97], s[0:1], v94, s34, v[112:113]
	s_waitcnt vmcnt(31)
	ds_write_b128 v96, v[62:65]
	v_mad_u64_u32 v[94:95], s[0:1], v98, s34, v[112:113]
	v_and_b32_e32 v63, 64, v230
	s_waitcnt vmcnt(30)
	ds_write_b128 v94, v[74:77]
	v_mad_u64_u32 v[76:77], s[0:1], v100, s34, v[112:113]
	v_mad_u64_u32 v[74:75], s[0:1], v102, s34, v[112:113]
	v_xor_b32_e32 v62, 1, v230
	v_add_u32_e32 v63, 64, v63
	v_cmp_lt_i32_e64 s[0:1], v62, v63
	s_waitcnt vmcnt(29)
	ds_write_b128 v76, v[78:81]
	s_waitcnt vmcnt(28)
	ds_write_b128 v74, v[82:85]
	v_cndmask_b32_e64 v62, v230, v62, s[0:1]
	v_lshlrev_b32_e32 v75, 2, v62
	v_xor_b32_e32 v62, 2, v230
	v_cmp_lt_i32_e64 s[0:1], v62, v63
	v_lshl_add_u32 v84, v110, 2, s22
	v_add_u32_e32 v85, s23, v108
	v_cndmask_b32_e64 v62, v230, v62, s[0:1]
	v_lshlrev_b32_e32 v77, 2, v62
	v_xor_b32_e32 v62, 4, v230
	v_cmp_lt_i32_e64 s[0:1], v62, v63
	v_lshlrev_b32_e32 v95, 1, v109
	v_cndmask_b32_e32 v107, v225, v229, vcc
	v_cndmask_b32_e64 v62, v230, v62, s[0:1]
	v_lshlrev_b32_e32 v78, 2, v62
	v_xor_b32_e32 v62, 8, v230
	v_cmp_lt_i32_e64 s[0:1], v62, v63
	s_waitcnt lgkmcnt(0)
	s_barrier
; #define LAS __attribute__((address_space(3)))
; __device__ __forceinline__ float bf_lo(unsigned u) { return __uint_as_float(u << 16); }
; __device__ __forceinline__ float bf_hi(unsigned u) { return __uint_as_float(u & 0xffff0000u); }
; __device__ __forceinline__ float bf2f(bf16_t b) { return __uint_as_float((unsigned)b << 16); }
; __device__ __forceinline__ bf16_t f2bf(float f) { return (bf16_t)(pk2(f, 0.f) & 0xffffu); }
; __device__ __forceinline__ float silu_acc(float x) { return x * frcp(1.0f + fexp(-x)); }
; __device__ __forceinline__ void mixer_out_phase(const Ctx& X, LAS unsigned char* lds, int layer, int tid, int wave, int lane) {
;     ...
;         for (int rt = 0; rt < 2; ++rt) {
;             f32x4 acc[4];
;             acc[0] = (f32x4){bf_lo(ov[rt][0].x), bf_hi(ov[rt][0].x), bf_lo(ov[rt][0].y), bf_hi(ov[rt][0].y)}; acc[1] = (f32x4){bf_lo(ov[rt][0].z), bf_hi(ov[rt][0].z), bf_lo(ov[rt][0].w), bf_hi(ov[rt][0].w)};
;             acc[2] = (f32x4){bf_lo(ov[rt][1].x), bf_hi(ov[rt][1].x), bf_lo(ov[rt][1].y), bf_hi(ov[rt][1].y)}; acc[3] = (f32x4){bf_lo(ov[rt][1].z), bf_hi(ov[rt][1].z), bf_lo(ov[rt][1].w), bf_hi(ov[rt][1].w)};
; #pragma unroll
;             for (int ct = 0; ct < 4; ++ct)
; #pragma unroll
;                 for (int ks = 0; ks < 2; ++ks) acc[ct] = __builtin_amdgcn_mfma_f32_16x16x32_bf16(a[rt][ks], bb[ct][ks], acc[ct], 0, 0, 0);
; #pragma unroll
;             for (int j = 0; j < 4; ++j) {
;                 float sm = (acc[0][j] + acc[1][j]) + (acc[2][j] + acc[3][j]);
;                 sm += __shfl_xor(sm, 1); sm += __shfl_xor(sm, 2); sm += __shfl_xor(sm, 4); sm += __shfl_xor(sm, 8);
;                 const float mu = mixer == 0 ? sm * (1.f / 64.f) : 0.f;
;                 float d[4], s2 = 0.f;
; #pragma unroll
;                 for (int ct = 0; ct < 4; ++ct) { d[ct] = acc[ct][j] - mu; s2 += d[ct] * d[ct]; }
;                 s2 += __shfl_xor(s2, 1); s2 += __shfl_xor(s2, 2); s2 += __shfl_xor(s2, 4); s2 += __shfl_xor(s2, 8);
;                 const float rs = rsqrtf(s2 * (1.f / 64.f) + (mixer == 0 ? 1e-5f : 1e-6f));
;                 const int ii = 16 * (2 * half + rt) + 4 * q + j;
; #pragma unroll
;                 for (int ct = 0; ct < 4; ++ct) { LAS bf16_t* gp = GT + ii * GP + h * 64 + 16 * ct + r;
;                     const float y = d[ct] * rs * wv[ct] * silu_acc(bf2f(*gp));
;                     *gp = on ? f2bf(y) : (bf16_t)0; }
	s_waitcnt vmcnt(25)
	v_lshlrev_b32_e32 v80, 16, v54
	v_cndmask_b32_e64 v62, v230, v62, s[0:1]
	v_lshlrev_b32_e32 v79, 2, v62
	s_waitcnt vmcnt(24)
	v_lshlrev_b32_e32 v62, 16, v58
	v_and_b32_e32 v63, 0xffff0000, v58
	v_lshlrev_b32_e32 v64, 16, v59
	v_and_b32_e32 v65, 0xffff0000, v59
	v_lshlrev_b32_e32 v58, 16, v60
	v_and_b32_e32 v59, 0xffff0000, v60
	v_lshlrev_b32_e32 v60, 16, v61
	v_and_b32_e32 v61, 0xffff0000, v61
	v_and_b32_e32 v81, 0xffff0000, v54
	v_lshlrev_b32_e32 v82, 16, v55
	s_waitcnt vmcnt(14)
	v_mfma_f32_16x16x32_bf16 v[58:61], v[66:69], v[30:33], v[58:61]
	v_and_b32_e32 v83, 0xffff0000, v55
	v_lshlrev_b32_e32 v108, 16, v56
	v_and_b32_e32 v109, 0xffff0000, v56
	v_lshlrev_b32_e32 v110, 16, v57
	v_and_b32_e32 v111, 0xffff0000, v57
	v_mfma_f32_16x16x32_bf16 v[54:57], v[66:69], v[22:25], v[62:65]
	s_waitcnt vmcnt(12)
	v_mfma_f32_16x16x32_bf16 v[62:65], v[70:73], v[34:37], v[58:61]
	s_waitcnt vmcnt(10)
	v_mfma_f32_16x16x32_bf16 v[58:61], v[66:69], v[38:41], v[80:83]
	s_waitcnt vmcnt(6)
	v_mfma_f32_16x16x32_bf16 v[66:69], v[66:69], v[46:49], v[108:111]
	v_mfma_f32_16x16x32_bf16 v[54:57], v[70:73], v[26:29], v[54:57]
	v_mfma_f32_16x16x32_bf16 v[58:61], v[70:73], v[42:45], v[58:61]
	s_waitcnt vmcnt(4)
	v_mfma_f32_16x16x32_bf16 v[66:69], v[70:73], v[50:53], v[66:69]
	s_nop 4
	v_mov_b32_e32 v70, v54
	v_mov_b32_e32 v71, v58
	v_mov_b32_e32 v72, v62
	v_mov_b32_e32 v83, v58
	v_mov_b32_e32 v73, v66
	v_pk_add_f32 v[70:71], v[70:71], v[72:73]
	v_mov_b32_e32 v72, v54
	v_add_f32_e32 v70, v70, v71
	ds_bpermute_b32 v71, v75, v70
	v_mov_b32_e32 v73, v62
	v_mov_b32_e32 v82, v66
	s_waitcnt lgkmcnt(0)
	v_add_f32_e32 v70, v70, v71
	ds_bpermute_b32 v71, v77, v70
	s_waitcnt lgkmcnt(0)
	v_add_f32_e32 v70, v70, v71
	ds_bpermute_b32 v71, v78, v70
	s_waitcnt lgkmcnt(0)
	v_add_f32_e32 v70, v70, v71
	ds_bpermute_b32 v71, v79, v70
	s_waitcnt lgkmcnt(0)
	v_add_f32_e32 v70, v70, v71
	v_mul_f32_e32 v70, 0x3c800000, v70
	v_cndmask_b32_e32 v70, 0, v70, vcc
	v_pk_add_f32 v[72:73], v[72:73], v[70:71] op_sel_hi:[1,0] neg_lo:[0,1] neg_hi:[0,1]
	v_pk_add_f32 v[70:71], v[82:83], v[70:71] op_sel_hi:[1,0] neg_lo:[0,1] neg_hi:[0,1]
	v_pk_mul_f32 v[80:81], v[72:73], v[72:73]
	v_pk_mul_f32 v[82:83], v[70:71], v[70:71]
	v_add_f32_e32 v54, v80, v81
	v_add_f32_e32 v54, v83, v54
	v_add_f32_e32 v54, v82, v54
	ds_bpermute_b32 v58, v75, v54
	s_waitcnt lgkmcnt(0)
	v_add_f32_e32 v54, v54, v58
	ds_bpermute_b32 v58, v77, v54
	s_waitcnt lgkmcnt(0)
	v_add_f32_e32 v54, v54, v58
	ds_bpermute_b32 v58, v78, v54
	s_waitcnt lgkmcnt(0)
	v_add_f32_e32 v54, v54, v58
	ds_bpermute_b32 v58, v79, v54
	s_waitcnt lgkmcnt(0)
	v_add_f32_e32 v54, v54, v58
	v_fmamk_f32 v54, v54, 0x3c800000, v107
	v_cmp_gt_f32_e64 s[0:1], s3, v54
	v_mul_f32_e32 v58, 0x4b800000, v54
	s_nop 0
	v_cndmask_b32_e64 v54, v54, v58, s[0:1]
	v_rsq_f32_e32 v54, v54
	s_nop 0
	v_mul_f32_e32 v58, 0x45800000, v54
	v_cndmask_b32_e64 v58, v54, v58, s[0:1]
	v_mul_lo_u32 v54, v84, s34
	v_add3_u32 v54, v85, v95, v54
	ds_read_u16 v62, v54
	s_waitcnt lgkmcnt(0)
	v_lshlrev_b32_e32 v62, 16, v62
	v_mul_f32_e32 v66, 0xbfb8aa3b, v62
	v_exp_f32_e32 v66, v66
	s_nop 0
	v_add_f32_e32 v66, 1.0, v66
	v_rcp_f32_e32 v66, v66
	s_nop 0
	v_mul_f32_e32 v62, v66, v62
	v_mul_f32_e32 v66, v72, v58
	s_waitcnt vmcnt(3)
	v_mul_f32_e32 v66, v106, v66
	v_mul_f32_e32 v62, v62, v66
	v_cvt_pk_bf16_f32 v62, v62, v157
	ds_write_b16 v54, v62
	ds_read_u16 v62, v54 offset:32
	s_waitcnt lgkmcnt(0)
	v_lshlrev_b32_e32 v62, 16, v62
	v_mul_f32_e32 v66, 0xbfb8aa3b, v62
	v_exp_f32_e32 v66, v66
	s_nop 0
	v_add_f32_e32 v66, 1.0, v66
	v_rcp_f32_e32 v66, v66
	s_nop 0
	v_mul_f32_e32 v62, v66, v62
	v_mul_f32_e32 v66, v73, v58
	s_waitcnt vmcnt(2)
	v_mul_f32_e32 v66, v103, v66
	v_mul_f32_e32 v62, v62, v66
	v_cvt_pk_bf16_f32 v62, v62, v157
	ds_write_b16 v54, v62 offset:32
	ds_read_u16 v62, v54 offset:64
	s_waitcnt lgkmcnt(0)
	v_lshlrev_b32_e32 v62, 16, v62
	v_mul_f32_e32 v66, 0xbfb8aa3b, v62
	v_exp_f32_e32 v66, v66
	s_nop 0
	v_add_f32_e32 v66, 1.0, v66
	v_rcp_f32_e32 v66, v66
	s_nop 0
	v_mul_f32_e32 v62, v66, v62
	v_mul_f32_e32 v66, v71, v58
	s_waitcnt vmcnt(1)
	v_mul_f32_e32 v66, v101, v66
	v_mul_f32_e32 v62, v62, v66
	v_cvt_pk_bf16_f32 v62, v62, v157
	ds_write_b16 v54, v62 offset:64
	ds_read_u16 v62, v54 offset:96
	v_mul_f32_e32 v58, v70, v58
	s_waitcnt vmcnt(0)
	s_add_i32 s98, s10, s18
	s_cmpk_ge_u32 s98, 0x600
	s_cbranch_scc1 .LpfO_done
	s_lshr_b32 s99, s98, 9
	s_and_b32 s98, s98, 0x1ff
	s_lshr_b32 s100, s98, 7
	s_and_b32 s98, s98, 0x7f
	s_lshl_b32 s101, s99, 2
	s_add_u32 s101, s101, s100
	s_lshl_b32 s101, s101, 9
	s_add_u32 s101, s101, s98
	s_lshl_b32 s101, s101, 13
	s_cmp_eq_u32 s99, 2
	s_mul_i32 s99, s99, 0xc00
	s_cselect_b32 s32, 0x400, 0
	s_sub_u32 s99, s99, s32
	s_add_u32 s99, s99, 0x600
	s_lshl_b32 s100, s100, 13
	s_lshl_b32 s98, s98, 6
	s_add_u32 s98, s98, s100
	s_mul_i32 s98, s98, 0x1c00
	s_add_u32 s98, s98, s99
	v_and_b32_e32 v237, 0xff, v224
	v_lshrrev_b32_e32 v238, 2, v237
	v_and_b32_e32 v239, 3, v237
	v_lshlrev_b32_e32 v239, 7, v239
	v_mad_u32_u24 v238, v238, s71, v239
	v_lshrrev_b32_e32 v239, 6, v237
	v_and_b32_e32 v237, 63, v237
	v_lshlrev_b32_e32 v239, 20, v239
	v_lshl_or_b32 v237, v237, 7, v239
	v_readfirstlane_b32 s32, v224
	s_add_u32 s82, s76, s98
	s_addc_u32 s83, s77, 0
	s_cmpk_lt_u32 s32, 0x100
	s_cbranch_scc0 .LpfO_hi
	s_add_u32 s98, s101, 0x3500000
	s_add_u32 s98, s30, s98
	s_addc_u32 s99, s31, 0
	global_load_dword v234, v238, s[82:83]
	global_load_dword v234, v237, s[98:99]
	s_branch .LpfO_done
.LpfO_hi:
	s_add_u32 s82, s101, 0x19600000
	s_add_u32 s82, s30, s82
	s_addc_u32 s83, s31, 0
	s_add_u32 s98, s101, 0x1c600000
	s_add_u32 s98, s30, s98
	s_addc_u32 s99, s31, 0
	global_load_dword v234, v237, s[82:83]
	global_load_dword v234, v237, s[98:99]
; #define LAS __attribute__((address_space(3)))
; __device__ __forceinline__ float bf2f(bf16_t b) { return __uint_as_float((unsigned)b << 16); }
; __device__ __forceinline__ bf16_t f2bf(float f) { return (bf16_t)(pk2(f, 0.f) & 0xffffu); }
; __device__ __forceinline__ float silu_acc(float x) { return x * frcp(1.0f + fexp(-x)); }
; __device__ __forceinline__ void mixer_out_phase(const Ctx& X, LAS unsigned char* lds, int layer, int tid, int wave, int lane) {
;     ...
;             for (int j = 0; j < 4; ++j) {
;                 float sm = (acc[0][j] + acc[1][j]) + (acc[2][j] + acc[3][j]);
;                 sm += __shfl_xor(sm, 1); sm += __shfl_xor(sm, 2); sm += __shfl_xor(sm, 4); sm += __shfl_xor(sm, 8);
;                 const float mu = mixer == 0 ? sm * (1.f / 64.f) : 0.f;
;                 float d[4], s2 = 0.f;
; #pragma unroll
;                 for (int ct = 0; ct < 4; ++ct) { d[ct] = acc[ct][j] - mu; s2 += d[ct] * d[ct]; }
;                 s2 += __shfl_xor(s2, 1); s2 += __shfl_xor(s2, 2); s2 += __shfl_xor(s2, 4); s2 += __shfl_xor(s2, 8);
;                 const float rs = rsqrtf(s2 * (1.f / 64.f) + (mixer == 0 ? 1e-5f : 1e-6f));
;                 const int ii = 16 * (2 * half + rt) + 4 * q + j;
; #pragma unroll
;                 for (int ct = 0; ct < 4; ++ct) { LAS bf16_t* gp = GT + ii * GP + h * 64 + 16 * ct + r;
;                     const float y = d[ct] * rs * wv[ct] * silu_acc(bf2f(*gp));
;                     *gp = on ? f2bf(y) : (bf16_t)0; }
.LpfO_done:
	v_mul_f32_e32 v58, v99, v58
	s_waitcnt lgkmcnt(0)
	v_lshlrev_b32_e32 v62, 16, v62
	v_mul_f32_e32 v66, 0xbfb8aa3b, v62
	v_exp_f32_e32 v66, v66
	s_nop 0
	v_add_f32_e32 v66, 1.0, v66
	v_rcp_f32_e32 v66, v66
	s_nop 0
	v_mul_f32_e32 v62, v66, v62
	v_mul_f32_e32 v58, v62, v58
	v_cvt_pk_bf16_f32 v58, v58, v157
	ds_write_b16 v54, v58 offset:96
	v_mov_b32_e32 v58, v55
	v_mov_b32_e32 v66, v63
	v_pk_add_f32 v[70:71], v[58:59], v[66:67]
	s_nop 0
	v_add_f32_e32 v58, v70, v71
	ds_bpermute_b32 v62, v75, v58
	s_waitcnt lgkmcnt(0)
	v_add_f32_e32 v58, v58, v62
	ds_bpermute_b32 v62, v77, v58
	s_waitcnt lgkmcnt(0)
	v_add_f32_e32 v58, v58, v62
	ds_bpermute_b32 v62, v78, v58
	s_waitcnt lgkmcnt(0)
	v_add_f32_e32 v58, v58, v62
	ds_bpermute_b32 v62, v79, v58
	s_waitcnt lgkmcnt(0)
	v_add_f32_e32 v58, v58, v62
	v_mul_f32_e32 v58, 0x3c800000, v58
	v_cndmask_b32_e32 v66, 0, v58, vcc
	v_mov_b32_e32 v62, v55
	v_pk_add_f32 v[62:63], v[62:63], v[66:67] op_sel_hi:[1,0] neg_lo:[0,1] neg_hi:[0,1]
	v_mov_b32_e32 v58, v67
	v_pk_mul_f32 v[70:71], v[62:63], v[62:63]
	v_pk_add_f32 v[58:59], v[58:59], v[66:67] op_sel_hi:[1,0] neg_lo:[0,1] neg_hi:[0,1]
	v_add_f32_e32 v55, v70, v71
	v_pk_mul_f32 v[66:67], v[58:59], v[58:59]
	v_mov_b32_e32 v70, v68
	v_add_f32_e32 v55, v67, v55
	v_add_f32_e32 v55, v66, v55
	ds_bpermute_b32 v66, v75, v55
	v_mov_b32_e32 v71, v60
	s_waitcnt lgkmcnt(0)
	v_add_f32_e32 v55, v55, v66
	ds_bpermute_b32 v66, v77, v55
	s_waitcnt lgkmcnt(0)
	v_add_f32_e32 v55, v55, v66
	ds_bpermute_b32 v66, v78, v55
	s_waitcnt lgkmcnt(0)
	v_add_f32_e32 v55, v55, v66
	ds_bpermute_b32 v66, v79, v55
	s_waitcnt lgkmcnt(0)
	v_add_f32_e32 v55, v55, v66
	v_fmamk_f32 v55, v55, 0x3c800000, v107
	v_cmp_gt_f32_e64 s[0:1], s3, v55
	v_mul_f32_e32 v66, 0x4b800000, v55
	s_nop 0
	v_cndmask_b32_e64 v55, v55, v66, s[0:1]
	v_rsq_f32_e32 v55, v55
	s_nop 0
	v_mul_f32_e32 v66, 0x45800000, v55
	v_cndmask_b32_e64 v55, v55, v66, s[0:1]
	ds_read_u16 v66, v54 offset:528
	v_mul_f32_e32 v62, v62, v55
	v_mul_f32_e32 v62, v106, v62
	v_mul_f32_e32 v63, v63, v55
	v_mul_f32_e32 v63, v103, v63
	s_waitcnt lgkmcnt(0)
	v_lshlrev_b32_e32 v66, 16, v66
	v_mul_f32_e32 v67, 0xbfb8aa3b, v66
	v_exp_f32_e32 v67, v67
	v_mul_f32_e32 v59, v59, v55
	v_mul_f32_e32 v59, v101, v59
	v_mul_f32_e32 v55, v58, v55
	v_add_f32_e32 v67, 1.0, v67
	v_rcp_f32_e32 v67, v67
	v_mul_f32_e32 v55, v99, v55
	v_mov_b32_e32 v58, v56
	v_mul_f32_e32 v66, v67, v66
	v_mul_f32_e32 v62, v66, v62
	v_cvt_pk_bf16_f32 v62, v62, v157
	ds_write_b16 v54, v62 offset:528
	ds_read_u16 v62, v54 offset:560
	s_waitcnt lgkmcnt(0)
	v_lshlrev_b32_e32 v62, 16, v62
	v_mul_f32_e32 v66, 0xbfb8aa3b, v62
	v_exp_f32_e32 v66, v66
	s_nop 0
	v_add_f32_e32 v66, 1.0, v66
	v_rcp_f32_e32 v66, v66
	s_nop 0
	v_mul_f32_e32 v62, v66, v62
	v_mul_f32_e32 v62, v62, v63
	v_cvt_pk_bf16_f32 v62, v62, v157
	ds_write_b16 v54, v62 offset:560
	ds_read_u16 v62, v54 offset:592
	s_waitcnt lgkmcnt(0)
	v_lshlrev_b32_e32 v62, 16, v62
	v_mul_f32_e32 v63, 0xbfb8aa3b, v62
	v_exp_f32_e32 v63, v63
	s_nop 0
	v_add_f32_e32 v63, 1.0, v63
	v_rcp_f32_e32 v63, v63
	s_nop 0
	v_mul_f32_e32 v62, v63, v62
	v_mul_f32_e32 v59, v62, v59
	v_cvt_pk_bf16_f32 v59, v59, v157
	ds_write_b16 v54, v59 offset:592
	ds_read_u16 v59, v54 offset:624
	v_mov_b32_e32 v63, v68
	v_mov_b32_e32 v68, v65
	s_waitcnt lgkmcnt(0)
	v_lshlrev_b32_e32 v59, 16, v59
	v_mul_f32_e32 v62, 0xbfb8aa3b, v59
	v_exp_f32_e32 v62, v62
	s_nop 0
	v_add_f32_e32 v62, 1.0, v62
	v_rcp_f32_e32 v62, v62
	s_nop 0
	v_mul_f32_e32 v59, v62, v59
	v_mul_f32_e32 v55, v55, v59
	v_mov_b32_e32 v59, v60
	v_mov_b32_e32 v62, v64
	v_cvt_pk_bf16_f32 v55, v55, v157
	v_pk_add_f32 v[58:59], v[58:59], v[62:63]
	ds_write_b16 v54, v55 offset:624
	v_add_f32_e32 v55, v58, v59
	ds_bpermute_b32 v58, v75, v55
	v_mov_b32_e32 v62, v56
	v_mov_b32_e32 v63, v64
	v_mov_b32_e32 v64, v57
	s_waitcnt lgkmcnt(0)
	v_add_f32_e32 v55, v55, v58
	ds_bpermute_b32 v58, v77, v55
	s_waitcnt lgkmcnt(0)
	v_add_f32_e32 v55, v55, v58
	ds_bpermute_b32 v58, v78, v55
	s_waitcnt lgkmcnt(0)
	v_add_f32_e32 v55, v55, v58
	ds_bpermute_b32 v58, v79, v55
	s_waitcnt lgkmcnt(0)
	v_add_f32_e32 v55, v55, v58
	v_mul_f32_e32 v55, 0x3c800000, v55
	v_cndmask_b32_e32 v58, 0, v55, vcc
	v_pk_add_f32 v[62:63], v[62:63], v[58:59] op_sel_hi:[1,0] neg_lo:[0,1] neg_hi:[0,1]
	v_pk_add_f32 v[58:59], v[70:71], v[58:59] op_sel_hi:[1,0] neg_lo:[0,1] neg_hi:[0,1]
	v_pk_mul_f32 v[66:67], v[62:63], v[62:63]
	v_pk_mul_f32 v[70:71], v[58:59], v[58:59]
	v_add_f32_e32 v55, v66, v67
	v_add_f32_e32 v55, v71, v55
	v_add_f32_e32 v55, v70, v55
	ds_bpermute_b32 v56, v75, v55
	v_lshlrev_b32_e32 v66, 16, v17
	v_and_b32_e32 v67, 0xffff0000, v17
	s_waitcnt lgkmcnt(0)
	v_add_f32_e32 v55, v55, v56
	ds_bpermute_b32 v56, v77, v55
	s_waitcnt lgkmcnt(0)
	v_add_f32_e32 v55, v55, v56
	ds_bpermute_b32 v56, v78, v55
	s_waitcnt lgkmcnt(0)
	v_add_f32_e32 v55, v55, v56
	ds_bpermute_b32 v56, v79, v55
	s_waitcnt lgkmcnt(0)
	v_add_f32_e32 v55, v55, v56
	v_fmamk_f32 v55, v55, 0x3c800000, v107
	v_cmp_gt_f32_e64 s[0:1], s3, v55
	v_mul_f32_e32 v56, 0x4b800000, v55
	s_nop 0
	v_cndmask_b32_e64 v55, v55, v56, s[0:1]
	v_rsq_f32_e32 v55, v55
	s_nop 0
	v_mul_f32_e32 v56, 0x45800000, v55
	v_cndmask_b32_e64 v55, v55, v56, s[0:1]
	ds_read_u16 v56, v54 offset:1056
	v_mul_f32_e32 v59, v59, v55
	v_mul_f32_e32 v59, v101, v59
	s_waitcnt lgkmcnt(0)
	v_lshlrev_b32_e32 v56, 16, v56
	v_mul_f32_e32 v60, 0xbfb8aa3b, v56
	v_exp_f32_e32 v60, v60
	s_nop 0
	v_add_f32_e32 v60, 1.0, v60
	v_rcp_f32_e32 v60, v60
	s_nop 0
	v_mul_f32_e32 v56, v60, v56
	v_mul_f32_e32 v60, v62, v55
	v_mul_f32_e32 v60, v106, v60
	v_mul_f32_e32 v56, v56, v60
	v_cvt_pk_bf16_f32 v56, v56, v157
	ds_write_b16 v54, v56 offset:1056
	ds_read_u16 v56, v54 offset:1088
	s_waitcnt lgkmcnt(0)
; #define LAS __attribute__((address_space(3)))
; __device__ __forceinline__ float bf_lo(unsigned u) { return __uint_as_float(u << 16); }
; __device__ __forceinline__ float bf_hi(unsigned u) { return __uint_as_float(u & 0xffff0000u); }
; __device__ __forceinline__ float bf2f(bf16_t b) { return __uint_as_float((unsigned)b << 16); }
; __device__ __forceinline__ bf16_t f2bf(float f) { return (bf16_t)(pk2(f, 0.f) & 0xffffu); }
; __device__ __forceinline__ float silu_acc(float x) { return x * frcp(1.0f + fexp(-x)); }
; __device__ __forceinline__ void mixer_out_phase(const Ctx& X, LAS unsigned char* lds, int layer, int tid, int wave, int lane) {
;     ...
;         for (int rt = 0; rt < 2; ++rt) {
;             f32x4 acc[4];
;             acc[0] = (f32x4){bf_lo(ov[rt][0].x), bf_hi(ov[rt][0].x), bf_lo(ov[rt][0].y), bf_hi(ov[rt][0].y)}; acc[1] = (f32x4){bf_lo(ov[rt][0].z), bf_hi(ov[rt][0].z), bf_lo(ov[rt][0].w), bf_hi(ov[rt][0].w)};
;             acc[2] = (f32x4){bf_lo(ov[rt][1].x), bf_hi(ov[rt][1].x), bf_lo(ov[rt][1].y), bf_hi(ov[rt][1].y)}; acc[3] = (f32x4){bf_lo(ov[rt][1].z), bf_hi(ov[rt][1].z), bf_lo(ov[rt][1].w), bf_hi(ov[rt][1].w)};
; #pragma unroll
;             for (int ct = 0; ct < 4; ++ct)
; #pragma unroll
;                 for (int ks = 0; ks < 2; ++ks) acc[ct] = __builtin_amdgcn_mfma_f32_16x16x32_bf16(a[rt][ks], bb[ct][ks], acc[ct], 0, 0, 0);
; #pragma unroll
;             for (int j = 0; j < 4; ++j) {
;                 float sm = (acc[0][j] + acc[1][j]) + (acc[2][j] + acc[3][j]);
;                 sm += __shfl_xor(sm, 1); sm += __shfl_xor(sm, 2); sm += __shfl_xor(sm, 4); sm += __shfl_xor(sm, 8);
;                 const float mu = mixer == 0 ? sm * (1.f / 64.f) : 0.f;
;                 float d[4], s2 = 0.f;
; #pragma unroll
;                 for (int ct = 0; ct < 4; ++ct) { d[ct] = acc[ct][j] - mu; s2 += d[ct] * d[ct]; }
;                 s2 += __shfl_xor(s2, 1); s2 += __shfl_xor(s2, 2); s2 += __shfl_xor(s2, 4); s2 += __shfl_xor(s2, 8);
;                 const float rs = rsqrtf(s2 * (1.f / 64.f) + (mixer == 0 ? 1e-5f : 1e-6f));
;                 const int ii = 16 * (2 * half + rt) + 4 * q + j;
; #pragma unroll
;                 for (int ct = 0; ct < 4; ++ct) { LAS bf16_t* gp = GT + ii * GP + h * 64 + 16 * ct + r;
;                     const float y = d[ct] * rs * wv[ct] * silu_acc(bf2f(*gp));
;                     *gp = on ? f2bf(y) : (bf16_t)0; }
	v_lshlrev_b32_e32 v56, 16, v56
	v_mul_f32_e32 v60, 0xbfb8aa3b, v56
	v_exp_f32_e32 v60, v60
	s_nop 0
	v_add_f32_e32 v60, 1.0, v60
	v_rcp_f32_e32 v60, v60
	s_nop 0
	v_mul_f32_e32 v56, v60, v56
	v_mul_f32_e32 v60, v63, v55
	v_mul_f32_e32 v60, v103, v60
	v_mul_f32_e32 v56, v56, v60
	v_cvt_pk_bf16_f32 v56, v56, v157
	ds_write_b16 v54, v56 offset:1088
	ds_read_u16 v56, v54 offset:1120
	v_mul_f32_e32 v55, v58, v55
	v_mul_f32_e32 v55, v99, v55
	s_waitcnt lgkmcnt(0)
	v_lshlrev_b32_e32 v56, 16, v56
	v_mul_f32_e32 v60, 0xbfb8aa3b, v56
	v_exp_f32_e32 v60, v60
	s_nop 0
	v_add_f32_e32 v60, 1.0, v60
	v_rcp_f32_e32 v60, v60
	s_nop 0
	v_mul_f32_e32 v56, v60, v56
	v_mul_f32_e32 v56, v56, v59
	v_cvt_pk_bf16_f32 v56, v56, v157
	ds_write_b16 v54, v56 offset:1120
	ds_read_u16 v56, v54 offset:1152
	v_mov_b32_e32 v60, v57
	s_waitcnt lgkmcnt(0)
	v_lshlrev_b32_e32 v56, 16, v56
	v_mul_f32_e32 v59, 0xbfb8aa3b, v56
	v_exp_f32_e32 v59, v59
	s_nop 0
	v_add_f32_e32 v59, 1.0, v59
	v_rcp_f32_e32 v59, v59
	s_nop 0
	v_mul_f32_e32 v56, v59, v56
	v_mul_f32_e32 v55, v55, v56
	v_cvt_pk_bf16_f32 v55, v55, v157
	v_pk_add_f32 v[58:59], v[60:61], v[68:69]
	ds_write_b16 v54, v55 offset:1152
	v_add_f32_e32 v55, v58, v59
	ds_bpermute_b32 v56, v75, v55
	v_mov_b32_e32 v60, v69
	s_waitcnt lgkmcnt(0)
	v_add_f32_e32 v55, v55, v56
	ds_bpermute_b32 v56, v77, v55
	s_waitcnt lgkmcnt(0)
	v_add_f32_e32 v55, v55, v56
	ds_bpermute_b32 v56, v78, v55
	s_waitcnt lgkmcnt(0)
	v_add_f32_e32 v55, v55, v56
	ds_bpermute_b32 v56, v79, v55
	s_waitcnt lgkmcnt(0)
	v_add_f32_e32 v55, v55, v56
	v_mul_f32_e32 v55, 0x3c800000, v55
	v_cndmask_b32_e32 v56, 0, v55, vcc
	v_pk_add_f32 v[58:59], v[64:65], v[56:57] op_sel_hi:[1,0] neg_lo:[0,1] neg_hi:[0,1]
	v_pk_add_f32 v[56:57], v[60:61], v[56:57] op_sel_hi:[1,0] neg_lo:[0,1] neg_hi:[0,1]
	v_pk_mul_f32 v[62:63], v[58:59], v[58:59]
	v_pk_mul_f32 v[60:61], v[56:57], v[56:57]
	v_add_f32_e32 v55, v62, v63
	v_add_f32_e32 v55, v61, v55
	v_add_f32_e32 v55, v60, v55
	ds_bpermute_b32 v60, v75, v55
	v_lshlrev_b32_e32 v62, 16, v15
	v_and_b32_e32 v63, 0xffff0000, v15
	v_lshlrev_b32_e32 v64, 16, v16
	v_and_b32_e32 v65, 0xffff0000, v16
	s_waitcnt lgkmcnt(0)
	v_add_f32_e32 v55, v55, v60
	ds_bpermute_b32 v60, v77, v55
	s_waitcnt lgkmcnt(0)
	v_add_f32_e32 v55, v55, v60
	ds_bpermute_b32 v60, v78, v55
	s_waitcnt lgkmcnt(0)
	v_add_f32_e32 v55, v55, v60
	ds_bpermute_b32 v60, v79, v55
	s_waitcnt lgkmcnt(0)
	v_add_f32_e32 v55, v55, v60
	v_fmamk_f32 v55, v55, 0x3c800000, v107
	v_cmp_gt_f32_e64 s[0:1], s3, v55
	v_mul_f32_e32 v60, 0x4b800000, v55
	s_nop 0
	v_cndmask_b32_e64 v55, v55, v60, s[0:1]
	v_rsq_f32_e32 v55, v55
	s_nop 0
	v_mul_f32_e32 v60, 0x45800000, v55
	v_cndmask_b32_e64 v55, v55, v60, s[0:1]
	ds_read_u16 v60, v54 offset:1584
	v_mul_f32_e32 v58, v58, v55
	v_mul_f32_e32 v58, v106, v58
	v_mul_f32_e32 v59, v59, v55
	v_mul_f32_e32 v59, v103, v59
	s_waitcnt lgkmcnt(0)
	v_lshlrev_b32_e32 v60, 16, v60
	v_mul_f32_e32 v61, 0xbfb8aa3b, v60
	v_exp_f32_e32 v61, v61
	v_mul_f32_e32 v57, v57, v55
	v_mul_f32_e32 v57, v101, v57
	v_mul_f32_e32 v55, v56, v55
	v_add_f32_e32 v61, 1.0, v61
	v_rcp_f32_e32 v61, v61
	v_mul_f32_e32 v55, v99, v55
	v_lshlrev_b32_e32 v56, 16, v18
	v_mul_f32_e32 v60, v61, v60
	v_mul_f32_e32 v58, v60, v58
	v_cvt_pk_bf16_f32 v58, v58, v157
	ds_write_b16 v54, v58 offset:1584
	ds_read_u16 v58, v54 offset:1616
	v_and_b32_e32 v61, 0xffff0000, v14
	s_waitcnt lgkmcnt(0)
	v_lshlrev_b32_e32 v58, 16, v58
	v_mul_f32_e32 v60, 0xbfb8aa3b, v58
	v_exp_f32_e32 v60, v60
	s_nop 0
	v_add_f32_e32 v60, 1.0, v60
	v_rcp_f32_e32 v60, v60
	s_nop 0
	v_mul_f32_e32 v58, v60, v58
	v_mul_f32_e32 v58, v58, v59
	v_cvt_pk_bf16_f32 v58, v58, v157
	ds_write_b16 v54, v58 offset:1616
	ds_read_u16 v58, v54 offset:1648
	v_lshlrev_b32_e32 v60, 16, v14
	s_waitcnt lgkmcnt(0)
	v_lshlrev_b32_e32 v58, 16, v58
	v_mul_f32_e32 v59, 0xbfb8aa3b, v58
	v_exp_f32_e32 v59, v59
	s_nop 0
	v_add_f32_e32 v59, 1.0, v59
	v_rcp_f32_e32 v59, v59
	s_nop 0
	v_mul_f32_e32 v58, v59, v58
	v_mul_f32_e32 v57, v58, v57
	v_cvt_pk_bf16_f32 v57, v57, v157
	ds_write_b16 v54, v57 offset:1648
	ds_read_u16 v57, v54 offset:1680
	v_and_b32_e32 v59, 0xffff0000, v19
	s_waitcnt lgkmcnt(0)
	v_lshlrev_b32_e32 v57, 16, v57
	v_mul_f32_e32 v58, 0xbfb8aa3b, v57
	v_exp_f32_e32 v58, v58
	s_nop 0
	v_add_f32_e32 v58, 1.0, v58
	v_rcp_f32_e32 v58, v58
	s_nop 0
	v_mul_f32_e32 v57, v58, v57
	v_mul_f32_e32 v55, v55, v57
	v_and_b32_e32 v57, 0xffff0000, v18
	v_lshlrev_b32_e32 v58, 16, v19
	v_lshlrev_b32_e32 v18, 16, v20
	v_and_b32_e32 v19, 0xffff0000, v20
	v_lshlrev_b32_e32 v20, 16, v21
	v_and_b32_e32 v21, 0xffff0000, v21
	v_mfma_f32_16x16x32_bf16 v[14:17], v[6:9], v[22:25], v[56:59]
	v_cvt_pk_bf16_f32 v55, v55, v157
	ds_write_b16 v54, v55 offset:1680
	v_mfma_f32_16x16x32_bf16 v[18:21], v[6:9], v[30:33], v[18:21]
	v_mfma_f32_16x16x32_bf16 v[22:25], v[10:13], v[34:37], v[18:21]
	v_mfma_f32_16x16x32_bf16 v[18:21], v[6:9], v[38:41], v[60:63]
	v_mfma_f32_16x16x32_bf16 v[6:9], v[6:9], v[46:49], v[64:67]
	v_mfma_f32_16x16x32_bf16 v[14:17], v[10:13], v[26:29], v[14:17]
	v_mfma_f32_16x16x32_bf16 v[18:21], v[10:13], v[42:45], v[18:21]
	v_mfma_f32_16x16x32_bf16 v[6:9], v[10:13], v[50:53], v[6:9]
	s_nop 5
	v_mov_b32_e32 v10, v14
	v_mov_b32_e32 v11, v18
	v_mov_b32_e32 v12, v22
	v_mov_b32_e32 v29, v18
	v_mov_b32_e32 v13, v6
	v_pk_add_f32 v[10:11], v[10:11], v[12:13]
	v_mov_b32_e32 v12, v14
	v_add_f32_e32 v10, v10, v11
	ds_bpermute_b32 v11, v75, v10
	v_mov_b32_e32 v13, v22
	v_mov_b32_e32 v28, v6
	v_mov_b32_e32 v22, v15
	s_waitcnt lgkmcnt(0)
	v_add_f32_e32 v10, v10, v11
	ds_bpermute_b32 v11, v77, v10
	s_waitcnt lgkmcnt(0)
	v_add_f32_e32 v10, v10, v11
	ds_bpermute_b32 v11, v78, v10
	s_waitcnt lgkmcnt(0)
; #define LAS __attribute__((address_space(3)))
; __device__ __forceinline__ float bf2f(bf16_t b) { return __uint_as_float((unsigned)b << 16); }
; __device__ __forceinline__ bf16_t f2bf(float f) { return (bf16_t)(pk2(f, 0.f) & 0xffffu); }
; __device__ __forceinline__ float silu_acc(float x) { return x * frcp(1.0f + fexp(-x)); }
; __device__ __forceinline__ void mixer_out_phase(const Ctx& X, LAS unsigned char* lds, int layer, int tid, int wave, int lane) {
;     ...
;             for (int j = 0; j < 4; ++j) {
;                 float sm = (acc[0][j] + acc[1][j]) + (acc[2][j] + acc[3][j]);
;                 sm += __shfl_xor(sm, 1); sm += __shfl_xor(sm, 2); sm += __shfl_xor(sm, 4); sm += __shfl_xor(sm, 8);
;                 const float mu = mixer == 0 ? sm * (1.f / 64.f) : 0.f;
;                 float d[4], s2 = 0.f;
; #pragma unroll
;                 for (int ct = 0; ct < 4; ++ct) { d[ct] = acc[ct][j] - mu; s2 += d[ct] * d[ct]; }
;                 s2 += __shfl_xor(s2, 1); s2 += __shfl_xor(s2, 2); s2 += __shfl_xor(s2, 4); s2 += __shfl_xor(s2, 8);
;                 const float rs = rsqrtf(s2 * (1.f / 64.f) + (mixer == 0 ? 1e-5f : 1e-6f));
;                 const int ii = 16 * (2 * half + rt) + 4 * q + j;
; #pragma unroll
;                 for (int ct = 0; ct < 4; ++ct) { LAS bf16_t* gp = GT + ii * GP + h * 64 + 16 * ct + r;
;                     const float y = d[ct] * rs * wv[ct] * silu_acc(bf2f(*gp));
;                     *gp = on ? f2bf(y) : (bf16_t)0; }
	v_add_f32_e32 v10, v10, v11
	ds_bpermute_b32 v11, v79, v10
	s_waitcnt lgkmcnt(0)
	v_add_f32_e32 v10, v10, v11
	v_mul_f32_e32 v10, 0x3c800000, v10
	v_cndmask_b32_e32 v10, 0, v10, vcc
	v_pk_add_f32 v[12:13], v[12:13], v[10:11] op_sel_hi:[1,0] neg_lo:[0,1] neg_hi:[0,1]
	v_pk_add_f32 v[10:11], v[28:29], v[10:11] op_sel_hi:[1,0] neg_lo:[0,1] neg_hi:[0,1]
	v_pk_mul_f32 v[26:27], v[12:13], v[12:13]
	v_pk_mul_f32 v[28:29], v[10:11], v[10:11]
	v_add_f32_e32 v6, v26, v27
	v_add_f32_e32 v6, v29, v6
	v_add_f32_e32 v6, v28, v6
	ds_bpermute_b32 v14, v75, v6
	s_waitcnt lgkmcnt(0)
	v_add_f32_e32 v6, v6, v14
	ds_bpermute_b32 v14, v77, v6
	s_waitcnt lgkmcnt(0)
	v_add_f32_e32 v6, v6, v14
	ds_bpermute_b32 v14, v78, v6
	s_waitcnt lgkmcnt(0)
	v_add_f32_e32 v6, v6, v14
	ds_bpermute_b32 v14, v79, v6
	s_waitcnt lgkmcnt(0)
	v_add_f32_e32 v6, v6, v14
	v_fmamk_f32 v6, v6, 0x3c800000, v107
	v_cmp_gt_f32_e64 s[0:1], s3, v6
	v_mul_f32_e32 v14, 0x4b800000, v6
	s_nop 0
	v_cndmask_b32_e64 v6, v6, v14, s[0:1]
	v_rsq_f32_e32 v6, v6
	s_nop 0
	v_mul_f32_e32 v14, 0x45800000, v6
	v_cndmask_b32_e64 v6, v6, v14, s[0:1]
	ds_read_u16 v14, v54 offset:8448
	v_mul_f32_e32 v12, v12, v6
	v_mul_f32_e32 v12, v106, v12
	v_mul_f32_e32 v13, v13, v6
	v_mul_f32_e32 v13, v103, v13
	s_waitcnt lgkmcnt(0)
	v_lshlrev_b32_e32 v14, 16, v14
	v_mul_f32_e32 v18, 0xbfb8aa3b, v14
	v_exp_f32_e32 v18, v18
	v_mul_f32_e32 v11, v11, v6
	v_mul_f32_e32 v11, v101, v11
	v_mul_f32_e32 v6, v10, v6
	v_add_f32_e32 v18, 1.0, v18
	v_rcp_f32_e32 v18, v18
	v_mul_f32_e32 v6, v99, v6
	v_mul_f32_e32 v14, v18, v14
	v_mul_f32_e32 v12, v14, v12
	v_cvt_pk_bf16_f32 v12, v12, v157
	ds_write_b16 v54, v12 offset:8448
	ds_read_u16 v12, v54 offset:8480
	v_mov_b32_e32 v18, v15
	s_waitcnt lgkmcnt(0)
	v_lshlrev_b32_e32 v12, 16, v12
	v_mul_f32_e32 v14, 0xbfb8aa3b, v12
	v_exp_f32_e32 v14, v14
	s_nop 0
	v_add_f32_e32 v14, 1.0, v14
	v_rcp_f32_e32 v14, v14
	s_nop 0
	v_mul_f32_e32 v12, v14, v12
	v_mul_f32_e32 v12, v12, v13
	v_cvt_pk_bf16_f32 v12, v12, v157
	ds_write_b16 v54, v12 offset:8480
	ds_read_u16 v12, v54 offset:8512
	s_waitcnt lgkmcnt(0)
	v_lshlrev_b32_e32 v12, 16, v12
	v_mul_f32_e32 v13, 0xbfb8aa3b, v12
	v_exp_f32_e32 v13, v13
	s_nop 0
	v_add_f32_e32 v13, 1.0, v13
	v_rcp_f32_e32 v13, v13
	s_nop 0
	v_mul_f32_e32 v12, v13, v12
	v_mul_f32_e32 v11, v12, v11
	v_cvt_pk_bf16_f32 v11, v11, v157
	ds_write_b16 v54, v11 offset:8512
	ds_read_u16 v11, v54 offset:8544
	s_waitcnt lgkmcnt(0)
	v_lshlrev_b32_e32 v11, 16, v11
	v_mul_f32_e32 v12, 0xbfb8aa3b, v11
	v_exp_f32_e32 v12, v12
	s_nop 0
	v_add_f32_e32 v12, 1.0, v12
	v_rcp_f32_e32 v12, v12
	s_nop 0
	v_mul_f32_e32 v11, v12, v11
	v_mul_f32_e32 v6, v11, v6
	v_cvt_pk_bf16_f32 v6, v6, v157
	ds_write_b16 v54, v6 offset:8544
	v_mov_b32_e32 v6, v23
	v_pk_add_f32 v[10:11], v[18:19], v[6:7]
	v_mov_b32_e32 v18, v7
	v_add_f32_e32 v6, v10, v11
	ds_bpermute_b32 v10, v75, v6
	s_waitcnt lgkmcnt(0)
	v_add_f32_e32 v6, v6, v10
	ds_bpermute_b32 v10, v77, v6
	s_waitcnt lgkmcnt(0)
	v_add_f32_e32 v6, v6, v10
	ds_bpermute_b32 v10, v78, v6
	s_waitcnt lgkmcnt(0)
	v_add_f32_e32 v6, v6, v10
	ds_bpermute_b32 v10, v79, v6
	s_waitcnt lgkmcnt(0)
	v_add_f32_e32 v6, v6, v10
	v_mul_f32_e32 v6, 0x3c800000, v6
	v_cndmask_b32_e32 v6, 0, v6, vcc
	v_pk_add_f32 v[10:11], v[22:23], v[6:7] op_sel_hi:[1,0] neg_lo:[0,1] neg_hi:[0,1]
	v_pk_add_f32 v[6:7], v[18:19], v[6:7] op_sel_hi:[1,0] neg_lo:[0,1] neg_hi:[0,1]
	v_pk_mul_f32 v[12:13], v[10:11], v[10:11]
	v_pk_mul_f32 v[14:15], v[6:7], v[6:7]
	v_add_f32_e32 v12, v12, v13
	v_add_f32_e32 v12, v15, v12
	v_add_f32_e32 v12, v14, v12
	ds_bpermute_b32 v13, v75, v12
	v_mov_b32_e32 v15, v20
	s_waitcnt lgkmcnt(0)
	v_add_f32_e32 v12, v12, v13
	ds_bpermute_b32 v13, v77, v12
	s_waitcnt lgkmcnt(0)
	v_add_f32_e32 v12, v12, v13
	ds_bpermute_b32 v13, v78, v12
	s_waitcnt lgkmcnt(0)
	v_add_f32_e32 v12, v12, v13
	ds_bpermute_b32 v13, v79, v12
	s_waitcnt lgkmcnt(0)
	v_add_f32_e32 v12, v12, v13
	v_fmamk_f32 v12, v12, 0x3c800000, v107
	v_cmp_gt_f32_e64 s[0:1], s3, v12
	v_mul_f32_e32 v13, 0x4b800000, v12
	s_nop 0
	v_cndmask_b32_e64 v12, v12, v13, s[0:1]
	v_rsq_f32_e32 v12, v12
	s_nop 0
	v_mul_f32_e32 v13, 0x45800000, v12
	v_cndmask_b32_e64 v12, v12, v13, s[0:1]
	ds_read_u16 v13, v54 offset:8976
	v_mul_f32_e32 v10, v10, v12
	v_mul_f32_e32 v10, v106, v10
	v_mul_f32_e32 v11, v11, v12
	v_mul_f32_e32 v11, v103, v11
	s_waitcnt lgkmcnt(0)
	v_lshlrev_b32_e32 v13, 16, v13
	v_mul_f32_e32 v14, 0xbfb8aa3b, v13
	v_exp_f32_e32 v14, v14
	v_mul_f32_e32 v7, v7, v12
	v_mul_f32_e32 v7, v101, v7
	v_mul_f32_e32 v6, v6, v12
	v_add_f32_e32 v14, 1.0, v14
	v_rcp_f32_e32 v14, v14
	v_mul_f32_e32 v6, v99, v6
	v_mul_f32_e32 v13, v14, v13
	v_mul_f32_e32 v10, v13, v10
	v_cvt_pk_bf16_f32 v10, v10, v157
	ds_write_b16 v54, v10 offset:8976
	ds_read_u16 v10, v54 offset:9008
	v_mov_b32_e32 v14, v8
	s_waitcnt lgkmcnt(0)
	v_lshlrev_b32_e32 v10, 16, v10
	v_mul_f32_e32 v13, 0xbfb8aa3b, v10
	v_exp_f32_e32 v13, v13
	s_nop 0
	v_add_f32_e32 v13, 1.0, v13
	v_rcp_f32_e32 v13, v13
	s_nop 0
	v_mul_f32_e32 v10, v13, v10
	v_mul_f32_e32 v10, v10, v11
	v_cvt_pk_bf16_f32 v10, v10, v157
	ds_write_b16 v54, v10 offset:9008
	ds_read_u16 v10, v54 offset:9040
	s_waitcnt lgkmcnt(0)
	v_lshlrev_b32_e32 v10, 16, v10
	v_mul_f32_e32 v11, 0xbfb8aa3b, v10
	v_exp_f32_e32 v11, v11
	s_nop 0
	v_add_f32_e32 v11, 1.0, v11
	v_rcp_f32_e32 v11, v11
	s_nop 0
	v_mul_f32_e32 v10, v11, v10
	v_mul_f32_e32 v7, v10, v7
	v_cvt_pk_bf16_f32 v7, v7, v157
	ds_write_b16 v54, v7 offset:9040
	ds_read_u16 v7, v54 offset:9072
	v_mov_b32_e32 v11, v8
	s_waitcnt lgkmcnt(0)
; #define LAS __attribute__((address_space(3)))
; __device__ __forceinline__ float bf2f(bf16_t b) { return __uint_as_float((unsigned)b << 16); }
; __device__ __forceinline__ bf16_t f2bf(float f) { return (bf16_t)(pk2(f, 0.f) & 0xffffu); }
; __device__ __forceinline__ float silu_acc(float x) { return x * frcp(1.0f + fexp(-x)); }
; #define LBAR() do { asm volatile("s_waitcnt lgkmcnt(0)" ::: "memory"); __builtin_amdgcn_s_barrier(); asm volatile("" ::: "memory"); } while (0)
; __device__ __forceinline__ void mixer_out_phase(const Ctx& X, LAS unsigned char* lds, int layer, int tid, int wave, int lane) {
;     ...
;             for (int j = 0; j < 4; ++j) {
;                 float sm = (acc[0][j] + acc[1][j]) + (acc[2][j] + acc[3][j]);
;                 sm += __shfl_xor(sm, 1); sm += __shfl_xor(sm, 2); sm += __shfl_xor(sm, 4); sm += __shfl_xor(sm, 8);
;                 const float mu = mixer == 0 ? sm * (1.f / 64.f) : 0.f;
;                 float d[4], s2 = 0.f;
; #pragma unroll
;                 for (int ct = 0; ct < 4; ++ct) { d[ct] = acc[ct][j] - mu; s2 += d[ct] * d[ct]; }
;                 s2 += __shfl_xor(s2, 1); s2 += __shfl_xor(s2, 2); s2 += __shfl_xor(s2, 4); s2 += __shfl_xor(s2, 8);
;                 const float rs = rsqrtf(s2 * (1.f / 64.f) + (mixer == 0 ? 1e-5f : 1e-6f));
;                 const int ii = 16 * (2 * half + rt) + 4 * q + j;
; #pragma unroll
;                 for (int ct = 0; ct < 4; ++ct) { LAS bf16_t* gp = GT + ii * GP + h * 64 + 16 * ct + r;
;                     const float y = d[ct] * rs * wv[ct] * silu_acc(bf2f(*gp));
;                     *gp = on ? f2bf(y) : (bf16_t)0; }
;             }
;         }
;         LBAR();
	v_lshlrev_b32_e32 v7, 16, v7
	v_mul_f32_e32 v10, 0xbfb8aa3b, v7
	v_exp_f32_e32 v10, v10
	s_nop 0
	v_add_f32_e32 v10, 1.0, v10
	v_rcp_f32_e32 v10, v10
	s_nop 0
	v_mul_f32_e32 v7, v10, v7
	v_mul_f32_e32 v6, v6, v7
	v_cvt_pk_bf16_f32 v6, v6, v157
	ds_write_b16 v54, v6 offset:9072
	v_mov_b32_e32 v6, v16
	v_mov_b32_e32 v7, v20
	v_mov_b32_e32 v10, v24
	v_pk_add_f32 v[6:7], v[6:7], v[10:11]
	v_mov_b32_e32 v10, v16
	v_add_f32_e32 v6, v6, v7
	ds_bpermute_b32 v7, v75, v6
	v_mov_b32_e32 v11, v24
	v_mov_b32_e32 v20, v17
	v_mov_b32_e32 v24, v17
	s_waitcnt lgkmcnt(0)
	v_add_f32_e32 v6, v6, v7
	ds_bpermute_b32 v7, v77, v6
	s_waitcnt lgkmcnt(0)
	v_add_f32_e32 v6, v6, v7
	ds_bpermute_b32 v7, v78, v6
	s_waitcnt lgkmcnt(0)
	v_add_f32_e32 v6, v6, v7
	ds_bpermute_b32 v7, v79, v6
	s_waitcnt lgkmcnt(0)
	v_add_f32_e32 v6, v6, v7
	v_mul_f32_e32 v6, 0x3c800000, v6
	v_cndmask_b32_e32 v6, 0, v6, vcc
	v_pk_add_f32 v[10:11], v[10:11], v[6:7] op_sel_hi:[1,0] neg_lo:[0,1] neg_hi:[0,1]
	v_pk_add_f32 v[6:7], v[14:15], v[6:7] op_sel_hi:[1,0] neg_lo:[0,1] neg_hi:[0,1]
	v_pk_mul_f32 v[12:13], v[10:11], v[10:11]
	v_pk_mul_f32 v[14:15], v[6:7], v[6:7]
	v_add_f32_e32 v8, v12, v13
	v_add_f32_e32 v8, v15, v8
	v_add_f32_e32 v8, v14, v8
	ds_bpermute_b32 v12, v75, v8
	s_waitcnt lgkmcnt(0)
	v_add_f32_e32 v8, v8, v12
	ds_bpermute_b32 v12, v77, v8
	s_waitcnt lgkmcnt(0)
	v_add_f32_e32 v8, v8, v12
	ds_bpermute_b32 v12, v78, v8
	s_waitcnt lgkmcnt(0)
	v_add_f32_e32 v8, v8, v12
	ds_bpermute_b32 v12, v79, v8
	s_waitcnt lgkmcnt(0)
	v_add_f32_e32 v8, v8, v12
	v_fmamk_f32 v8, v8, 0x3c800000, v107
	v_cmp_gt_f32_e64 s[0:1], s3, v8
	v_mul_f32_e32 v12, 0x4b800000, v8
	s_nop 0
	v_cndmask_b32_e64 v8, v8, v12, s[0:1]
	v_rsq_f32_e32 v8, v8
	s_nop 0
	v_mul_f32_e32 v12, 0x45800000, v8
	v_cndmask_b32_e64 v8, v8, v12, s[0:1]
	ds_read_u16 v12, v54 offset:9504
	v_mul_f32_e32 v10, v10, v8
	v_mul_f32_e32 v10, v106, v10
	v_mul_f32_e32 v11, v11, v8
	v_mul_f32_e32 v11, v103, v11
	s_waitcnt lgkmcnt(0)
	v_lshlrev_b32_e32 v12, 16, v12
	v_mul_f32_e32 v13, 0xbfb8aa3b, v12
	v_exp_f32_e32 v13, v13
	v_mul_f32_e32 v7, v7, v8
	v_mul_f32_e32 v7, v101, v7
	v_mul_f32_e32 v6, v6, v8
	v_add_f32_e32 v13, 1.0, v13
	v_rcp_f32_e32 v13, v13
	v_mul_f32_e32 v6, v99, v6
	v_mov_b32_e32 v8, v25
	s_lshl_b32 s0, s11, 1
	v_mul_f32_e32 v12, v13, v12
	v_mul_f32_e32 v10, v12, v10
	v_cvt_pk_bf16_f32 v10, v10, v157
	ds_write_b16 v54, v10 offset:9504
	ds_read_u16 v10, v54 offset:9536
	s_add_u32 s0, s60, s0
	s_addc_u32 s1, s67, 0
	s_add_i32 s10, s10, s18
	s_cmpk_lt_i32 s10, 0x600
	s_waitcnt lgkmcnt(0)
	v_lshlrev_b32_e32 v10, 16, v10
	v_mul_f32_e32 v12, 0xbfb8aa3b, v10
	v_exp_f32_e32 v12, v12
	s_nop 0
	v_add_f32_e32 v12, 1.0, v12
	v_rcp_f32_e32 v12, v12
	s_nop 0
	v_mul_f32_e32 v10, v12, v10
	v_mul_f32_e32 v10, v10, v11
	v_cvt_pk_bf16_f32 v10, v10, v157
	ds_write_b16 v54, v10 offset:9536
	ds_read_u16 v10, v54 offset:9568
	s_waitcnt lgkmcnt(0)
	v_lshlrev_b32_e32 v10, 16, v10
	v_mul_f32_e32 v11, 0xbfb8aa3b, v10
	v_exp_f32_e32 v11, v11
	s_nop 0
	v_add_f32_e32 v11, 1.0, v11
	v_rcp_f32_e32 v11, v11
	s_nop 0
	v_mul_f32_e32 v10, v11, v10
	v_mul_f32_e32 v7, v10, v7
	v_cvt_pk_bf16_f32 v7, v7, v157
	ds_write_b16 v54, v7 offset:9568
	ds_read_u16 v7, v54 offset:9600
	s_waitcnt lgkmcnt(0)
	v_lshlrev_b32_e32 v7, 16, v7
	v_mul_f32_e32 v10, 0xbfb8aa3b, v7
	v_exp_f32_e32 v10, v10
	s_nop 0
	v_add_f32_e32 v10, 1.0, v10
	v_rcp_f32_e32 v10, v10
	s_nop 0
	v_mul_f32_e32 v7, v10, v7
	v_mul_f32_e32 v6, v6, v7
	v_cvt_pk_bf16_f32 v6, v6, v157
	ds_write_b16 v54, v6 offset:9600
	v_pk_add_f32 v[6:7], v[20:21], v[8:9]
	v_mov_b32_e32 v20, v9
	v_add_f32_e32 v6, v6, v7
	ds_bpermute_b32 v7, v75, v6
	s_waitcnt lgkmcnt(0)
	v_add_f32_e32 v6, v6, v7
	ds_bpermute_b32 v7, v77, v6
	s_waitcnt lgkmcnt(0)
	v_add_f32_e32 v6, v6, v7
	ds_bpermute_b32 v7, v78, v6
	s_waitcnt lgkmcnt(0)
	v_add_f32_e32 v6, v6, v7
	ds_bpermute_b32 v7, v79, v6
	s_waitcnt lgkmcnt(0)
	v_add_f32_e32 v6, v6, v7
	v_mul_f32_e32 v6, 0x3c800000, v6
	v_cndmask_b32_e32 v6, 0, v6, vcc
	v_pk_add_f32 v[10:11], v[24:25], v[6:7] op_sel_hi:[1,0] neg_lo:[0,1] neg_hi:[0,1]
	v_pk_add_f32 v[6:7], v[20:21], v[6:7] op_sel_hi:[1,0] neg_lo:[0,1] neg_hi:[0,1]
	v_pk_mul_f32 v[12:13], v[10:11], v[10:11]
	v_pk_mul_f32 v[8:9], v[6:7], v[6:7]
	v_add_f32_e32 v12, v12, v13
	v_add_f32_e32 v9, v9, v12
	v_add_f32_e32 v8, v8, v9
	ds_bpermute_b32 v9, v75, v8
	s_waitcnt lgkmcnt(0)
	v_add_f32_e32 v8, v8, v9
	ds_bpermute_b32 v9, v77, v8
	s_waitcnt lgkmcnt(0)
	v_add_f32_e32 v8, v8, v9
	ds_bpermute_b32 v9, v78, v8
	s_waitcnt lgkmcnt(0)
	v_add_f32_e32 v8, v8, v9
	ds_bpermute_b32 v9, v79, v8
	s_waitcnt lgkmcnt(0)
	v_add_f32_e32 v8, v8, v9
	v_fmac_f32_e32 v107, 0x3c800000, v8
	v_cmp_gt_f32_e32 vcc, s3, v107
	v_mul_f32_e32 v8, 0x4b800000, v107
	s_nop 0
	v_cndmask_b32_e32 v8, v107, v8, vcc
	v_rsq_f32_e32 v8, v8
	s_nop 0
	v_mul_f32_e32 v9, 0x45800000, v8
	v_cndmask_b32_e32 v8, v8, v9, vcc
	ds_read_u16 v9, v54 offset:10032
	v_mul_f32_e32 v10, v10, v8
	v_mul_f32_e32 v10, v106, v10
	v_mul_f32_e32 v7, v7, v8
	v_mul_f32_e32 v7, v101, v7
	s_waitcnt lgkmcnt(0)
	v_lshlrev_b32_e32 v9, 16, v9
	v_mul_f32_e32 v12, 0xbfb8aa3b, v9
	v_exp_f32_e32 v12, v12
	v_mul_f32_e32 v6, v6, v8
	v_mul_f32_e32 v6, v99, v6
	v_add_f32_e32 v12, 1.0, v12
	v_rcp_f32_e32 v12, v12
	s_nop 0
	v_mul_f32_e32 v9, v12, v9
	v_mul_f32_e32 v9, v9, v10
	v_cvt_pk_bf16_f32 v9, v9, v157
	ds_write_b16 v54, v9 offset:10032
	ds_read_u16 v9, v54 offset:10064
	v_lshlrev_b64 v[12:13], 11, v[92:93]
	s_waitcnt lgkmcnt(0)
	v_lshlrev_b32_e32 v9, 16, v9
	v_mul_f32_e32 v10, 0xbfb8aa3b, v9
	v_exp_f32_e32 v10, v10
	s_nop 0
	v_add_f32_e32 v10, 1.0, v10
	v_rcp_f32_e32 v10, v10
	s_nop 0
	v_mul_f32_e32 v9, v10, v9
	v_mul_f32_e32 v10, v11, v8
	v_mul_f32_e32 v10, v103, v10
	v_mul_f32_e32 v9, v9, v10
	v_cvt_pk_bf16_f32 v9, v9, v157
	ds_write_b16 v54, v9 offset:10064
	ds_read_u16 v9, v54 offset:10096
	s_waitcnt lgkmcnt(0)
	v_lshlrev_b32_e32 v9, 16, v9
	v_mul_f32_e32 v10, 0xbfb8aa3b, v9
	v_exp_f32_e32 v10, v10
	s_nop 0
	v_add_f32_e32 v10, 1.0, v10
	v_rcp_f32_e32 v10, v10
	s_nop 0
	v_mul_f32_e32 v9, v10, v9
	v_mul_f32_e32 v7, v9, v7
	v_cvt_pk_bf16_f32 v7, v7, v157
	ds_write_b16 v54, v7 offset:10096
	ds_read_u16 v7, v54 offset:10128
	v_lshl_add_u64 v[10:11], s[0:1], 0, v[156:157]
	v_lshl_add_u64 v[12:13], v[10:11], 0, v[12:13]
	s_waitcnt lgkmcnt(0)
	v_lshlrev_b32_e32 v7, 16, v7
	v_mul_f32_e32 v9, 0xbfb8aa3b, v7
	v_exp_f32_e32 v9, v9
	s_nop 0
	v_add_f32_e32 v9, 1.0, v9
	v_rcp_f32_e32 v9, v9
	s_nop 0
	v_mul_f32_e32 v7, v9, v7
	v_mul_f32_e32 v6, v6, v7
	v_cvt_pk_bf16_f32 v6, v6, v157
	ds_write_b16 v54, v6 offset:10128
	s_waitcnt lgkmcnt(0)
	s_barrier
; #define LAS __attribute__((address_space(3)))
; #define LBAR() do { asm volatile("s_waitcnt lgkmcnt(0)" ::: "memory"); __builtin_amdgcn_s_barrier(); asm volatile("" ::: "memory"); } while (0)
; __device__ __forceinline__ void mixer_out_phase(const Ctx& X, LAS unsigned char* lds, int layer, int tid, int wave, int lane) {
;     ...
;         LBAR();
; #pragma unroll
;         for (int n = 0; n < 4; ++n) { const int idx = tid + 512 * n; __builtin_nontemporal_store(*(const LAS u32x4*)(GT + (idx >> 5) * GP + (idx & 31) * 8), (u32x4*)(mix + (row0 + (idx >> 5)) * D + moff + (idx & 31) * 8)); }
;         LBAR();
;     }
	ds_read_b128 v[6:9], v96
	s_waitcnt lgkmcnt(0)
	global_store_dwordx4 v[12:13], v[6:9], off nt
	ds_read_b128 v[6:9], v94
	v_lshlrev_b64 v[12:13], 11, v[90:91]
	v_lshl_add_u64 v[12:13], v[10:11], 0, v[12:13]
	s_waitcnt lgkmcnt(0)
	global_store_dwordx4 v[12:13], v[6:9], off nt
	ds_read_b128 v[6:9], v76
	v_lshlrev_b64 v[12:13], 11, v[88:89]
	v_lshl_add_u64 v[12:13], v[10:11], 0, v[12:13]
	s_waitcnt lgkmcnt(0)
	global_store_dwordx4 v[12:13], v[6:9], off nt
	ds_read_b128 v[6:9], v74
	v_lshlrev_b64 v[12:13], 11, v[86:87]
	v_lshl_add_u64 v[10:11], v[10:11], 0, v[12:13]
	s_waitcnt lgkmcnt(0)
	global_store_dwordx4 v[10:11], v[6:9], off nt
	s_waitcnt lgkmcnt(0)
	s_barrier
	s_cbranch_scc1 .LBB0_888
	v_readlane_b32 s54, v255, 7
	v_readlane_b32 s56, v255, 9
	v_readlane_b32 s58, v255, 11
	v_readlane_b32 s48, v255, 13
	v_readlane_b32 s50, v255, 15
	v_readlane_b32 s52, v255, 17
	v_readlane_b32 s55, v255, 8
	v_readlane_b32 s57, v255, 10
	v_readlane_b32 s59, v255, 12
	v_readlane_b32 s49, v255, 14
	v_readlane_b32 s51, v255, 16
	v_readlane_b32 s53, v255, 18
	s_mov_b64 s[22:23], s[64:65]
	v_readlane_b32 s19, v255, 26

; #define PG8_STAGE(bufoff, gbase, voff) do { _Pragma("unroll") for (int _i = 0; _i < 2; ++_i) \
;         __builtin_amdgcn_global_load_lds((const unsigned*)((const char*)(gbase) + (voff)[_i]), (PG8_LAS unsigned*)(lds + (bufoff) + ldsw + _i * 8192), 16, 0, 0); } while (0)
; #define PG8_WAIT_V(n) asm volatile("s_waitcnt vmcnt(" #n ")" ::: "memory")
; #define PG8_BAR __builtin_amdgcn_s_barrier()
; template <class Epi, class Sched, bool ALIGN_EPI = false, bool SP2 = false>
; __device__ __forceinline__ void gemm_phase(PG8_LAS unsigned char* lds, const Gemm g, const Sched& S, const Epi& E) {
;     ...
;     for (int i = 0; i < 2; ++i) { int R, C; stage_rc(tid * 16 + i * 8192, R, C); const int Rb = Epi::PERM ? ((R & ~31) + perm32(R & 31)) : R;
;         voffA[i] = (unsigned)(R * K + C) * 2u; voffB[i] = (unsigned)(Rb * K + C) * 2u; }
;     const size_t kstep = (size_t)(BK * 2);
;     const size_t hstep = (size_t)HALF * K * 2;
;     const size_t tstep = 2 * hstep;
;     const unsigned ldsw = (unsigned)wid * 1024u;
;     const int aoff = lds_byte(wr * 64 + fr, fq * 8), boff = lds_byte(wc * 32 + fr, fq * 8);
;     ...
;     Unit cur, nxt; int ui = 0;
;     float rsv[8];
;     if (!S.next(0, cur)) return;
;     f32x4 acc[2][2][4][2];
; #pragma unroll
;     for (int a = 0; a < 2; ++a)
; #pragma unroll
;         for (int b = 0; b < 2; ++b)
; #pragma unroll
;             for (int m = 0; m < 4; ++m)
; #pragma unroll
;                 for (int n = 0; n < 2; ++n) acc[a][b][m][n] = (f32x4){0.f, 0.f, 0.f, 0.f};
;     bf16x8 At[4][2], B0[2][2], B1[2][2];
;     const char* cA = (const char*)g.A + (size_t)cur.pm * tstep; const char* cB = (const char*)g.Bt + (size_t)cur.pn * tstep;
;     S.a_ready(cur);
;     if constexpr (SP2) {
;         PG8_STAGE(PG8_SB(0, 0), cB, voffB); PG8_STAGE(PG8_SB(0, 1), cB + hstep, voffB); PG8_STAGE(PG8_SA(0, 0), cA, voffA); PG8_STAGE(PG8_SA(0, 1), cA + hstep, voffA);
;         if (wr == 1) PG8_BAR;
;         PG8_WAIT_V(2); PG8_BAR;
;         PG8_STAGE(PG8_SB(1, 0), cB + kstep, voffB); PG8_STAGE(PG8_SA(1, 0), cA + kstep, voffA); PG8_STAGE(PG8_SB(1, 1), cB + hstep + kstep, voffB);
.Lgs3_done:
	s_waitcnt vmcnt(0)
	s_branch .Lgs3_pad
	s_nop 0
	s_nop 0
	s_nop 0
	s_nop 0
	s_nop 0
	s_nop 0
	s_nop 0
	s_nop 0
	s_nop 0
	s_nop 0
	s_nop 0
	s_nop 0
	s_nop 0
	s_nop 0
	s_nop 0
	s_nop 0
	s_nop 0
	s_nop 0
	s_nop 0
	s_nop 0
	s_nop 0
	s_nop 0
	s_nop 0
	s_nop 0
	s_nop 0
	s_nop 0
	s_nop 0
	s_nop 0
	s_nop 0
	s_nop 0
	s_nop 0
	s_nop 0
	s_nop 0
	s_nop 0
	s_nop 0
	s_nop 0
	s_nop 0
	s_nop 0
	s_nop 0
	s_nop 0
	s_nop 0
	s_nop 0
	s_nop 0
	s_nop 0
	s_nop 0
	s_nop 0
	s_nop 0
	s_nop 0
	s_nop 0
	s_nop 0
	s_nop 0
	s_nop 0
	s_nop 0
	s_nop 0
	s_nop 0
	s_nop 0
	s_nop 0
	s_nop 0
	s_nop 0
	s_nop 0
	s_nop 0
	s_nop 0
	s_nop 0
	s_nop 0
	s_nop 0
	s_nop 0
	s_nop 0
	s_nop 0
	s_nop 0
	s_nop 0
	s_nop 0
	s_nop 0
	s_nop 0
	s_nop 0
	s_nop 0
	s_nop 0
	s_nop 0
	s_nop 0
	s_nop 0
	s_nop 0
	s_nop 0
	s_nop 0
	s_nop 0
	s_nop 0
	s_nop 0
	s_nop 0
	s_nop 0
	s_nop 0
	s_nop 0
	s_nop 0
	s_nop 0
	s_nop 0
	s_nop 0
	s_nop 0
	s_nop 0
	s_nop 0
	s_nop 0
	s_nop 0
	s_nop 0
	s_nop 0
	s_nop 0
	s_nop 0
	s_nop 0
	s_nop 0
	s_nop 0
	s_nop 0
	s_nop 0
	s_nop 0
	s_nop 0
	s_nop 0
	s_nop 0
	s_nop 0
	s_nop 0
	s_nop 0
	s_nop 0
	s_nop 0
	s_nop 0
	s_nop 0
	s_nop 0
	s_nop 0
	s_nop 0
	s_nop 0
	s_nop 0
	s_nop 0
	s_nop 0
	s_nop 0
	s_nop 0
	s_nop 0
	s_nop 0
	s_nop 0
.Lgs3_pad:
.LBB0_942:
	s_or_b64 exec, exec, s[0:1]
	s_and_b64 s[0:1], s[26:27], exec
	v_readlane_b32 s0, v253, 63
	v_readlane_b32 s1, v254, 0
	s_waitcnt vmcnt(0)
	v_mov_b32_e32 v10, v224
	s_waitcnt lgkmcnt(0)
	v_cndmask_b32_e64 v6, 0, 1, s[0:1]
	v_cmp_ne_u32_e64 s[4:5], 1, v6
	s_barrier
	s_nop 0
	v_writelane_b32 v255, s4, 32
	s_cselect_b32 s35, 0, s29
	s_cselect_b32 s34, 0, s28
	v_writelane_b32 v255, s5, 33
	s_andn2_b64 vcc, exec, s[0:1]
	v_readfirstlane_b32 s6, v10
	s_cbranch_vccnz .LBB0_1042
	v_lshlrev_b32_e32 v6, 4, v10
	v_add_u32_e32 v7, 0x2000, v6
	v_ashrrev_i32_e32 v8, 31, v7
	v_lshrrev_b32_e32 v8, 22, v8
	v_add_u32_e32 v8, v7, v8
	v_ashrrev_i32_e32 v11, 10, v8
	v_mul_i32_i24_e32 v8, 0x400, v11
	v_sub_u32_e32 v7, v7, v8
	v_lshrrev_b32_e32 v8, 4, v7
	v_bitop3_b32 v7, v8, v7, 32 bitop3:0x6c
	v_ashrrev_i32_e32 v8, 31, v7
	v_readlane_b32 s0, v254, 61
	v_lshrrev_b32_e32 v8, 26, v8
	v_readlane_b32 s1, v254, 62
	v_add_u32_e32 v8, v7, v8
	v_lshlrev_b32_e32 v9, 3, v11
	s_lshl_b64 s[0:1], s[0:1], 21
	v_readlane_b32 s4, v253, 54
	v_ashrrev_i32_e32 v12, 6, v8
	v_and_b32_e32 v9, -16, v9
	s_add_u32 s16, s4, s0
	v_readlane_b32 s0, v253, 55
	v_add_u32_e32 v9, v12, v9
	s_addc_u32 s19, s0, s1
	v_and_b32_e32 v13, 3, v12
	s_mov_b32 s0, 0x1fffe0
	v_lshrrev_b32_e32 v14, 2, v9
	v_lshlrev_b32_e32 v15, 1, v9
	v_and_b32_e32 v8, 0xc0, v8
	v_and_or_b32 v13, v9, s0, v13
	v_and_b32_e32 v14, 4, v14
	v_and_b32_e32 v15, 24, v15
	v_sub_u32_e32 v7, v7, v8
	v_or3_b32 v14, v13, v14, v15
	v_lshlrev_b32_e32 v13, 5, v11
	v_ashrrev_i16_sdwa v7, v228, sext(v7) dst_sel:DWORD dst_unused:UNUSED_PAD src0_sel:DWORD src1_sel:BYTE_0
	v_and_b32_e32 v15, 32, v13
	v_bfe_i32 v13, v7, 0, 16
	v_add_lshl_u32 v7, v15, v13, 1
	v_lshl_add_u32 v142, v14, 11, v7
	v_lshl_add_u32 v144, v9, 11, v7
	v_bfe_i32 v7, v10, 27, 1
	v_lshrrev_b32_e32 v7, 22, v7
	v_add_u32_e32 v7, v6, v7
	v_and_b32_e32 v7, 0xfffffc00, v7
	v_sub_u32_e32 v6, v6, v7
	v_lshrrev_b32_e32 v7, 4, v6
	v_ashrrev_i32_e32 v8, 31, v10
	v_bitop3_b32 v6, v7, v6, 32 bitop3:0x6c
	v_lshrrev_b32_e32 v8, 26, v8
	v_ashrrev_i32_e32 v7, 31, v6
	v_add_u32_e32 v8, v10, v8
	v_lshrrev_b32_e32 v7, 26, v7
	v_ashrrev_i32_e32 v15, 6, v8
	v_add_u32_e32 v7, v6, v7
	v_lshlrev_b32_e32 v8, 3, v15
	v_ashrrev_i32_e32 v14, 6, v7
	v_and_b32_e32 v8, -16, v8
	v_add_u32_e32 v8, v14, v8
	v_and_b32_e32 v9, 3, v14
	v_lshrrev_b32_e32 v16, 2, v8
	v_lshlrev_b32_e32 v17, 1, v8
	v_and_b32_e32 v7, 0xc0, v7
	s_ashr_i32 s8, s6, 6
	v_and_or_b32 v9, v8, s0, v9
	v_and_b32_e32 v16, 4, v16
	v_and_b32_e32 v17, 24, v17
	v_sub_u32_e32 v6, v6, v7
	s_ashr_i32 s7, s6, 8
	s_lshl_b32 s33, s8, 10
	v_or3_b32 v9, v9, v16, v17
	v_lshlrev_b32_e32 v16, 5, v15
	v_ashrrev_i16_sdwa v6, v228, sext(v6) dst_sel:DWORD dst_unused:UNUSED_PAD src0_sel:DWORD src1_sel:BYTE_0
	v_readlane_b32 s0, v254, 26
	v_and_b32_e32 v17, 32, v16
	v_bfe_i32 v16, v6, 0, 16
	v_readlane_b32 s1, v254, 27
	s_add_u32 s4, s16, s0
	v_add_lshl_u32 v6, v17, v16, 1
	s_addc_u32 s5, s19, s1
	s_add_i32 s80, s33, 0
	v_lshl_add_u32 v156, v9, 11, v6
	s_add_i32 m0, s80, 0x10000
	v_lshl_add_u32 v146, v8, 11, v6
	global_load_lds_dwordx4 v156, s[4:5]
	s_add_i32 m0, s80, 0x12000
	s_add_u32 s0, s4, 0x40000
	global_load_lds_dwordx4 v142, s[4:5]
	s_addc_u32 s1, s5, 0
	s_add_i32 m0, s80, 0x14000
	s_add_i32 s81, s80, 0x2000
	global_load_lds_dwordx4 v156, s[0:1]
	s_add_i32 m0, s80, 0x16000
	s_add_i32 s87, s80, 0x4000
	global_load_lds_dwordx4 v142, s[0:1]
	v_readlane_b32 s0, v254, 28
	s_mov_b32 m0, s80
	v_readlane_b32 s1, v254, 29
	s_add_i32 s88, s80, 0x6000
	v_mov_b32_e32 v143, v157
	s_cmp_eq_u32 s7, 1
	v_lshl_add_u64 v[6:7], s[4:5], 0, v[156:157]
	v_lshl_add_u64 v[8:9], s[4:5], 0, v[142:143]
	global_load_lds_dwordx4 v146, s[0:1]
	s_mov_b32 m0, s81
	s_nop 0
	global_load_lds_dwordx4 v144, s[0:1]
	v_readlane_b32 s0, v254, 30
	s_mov_b32 m0, s87
	v_readlane_b32 s1, v254, 31
	s_nop 4
	global_load_lds_dwordx4 v146, s[0:1]
	s_mov_b32 m0, s88
	s_nop 0
	global_load_lds_dwordx4 v144, s[0:1]
	s_cselect_b64 s[0:1], -1, 0
	s_cmp_lg_u32 s7, 1
	s_cbranch_scc1 .LBB0_945
	s_barrier
